# GEMM P4 K-loop: LDS-DMA via scalar base + 32-bit lane offset (no per-load 64-bit VALU adds), B reads via immediates
# speedup vs baseline: 1.0065x; 1.0065x over previous
.LBB0_807:
	ds_read_b128 v[154:157], v150
	ds_read_b128 v[158:161], v150 offset:1024
	ds_read_b128 v[162:165], v150 offset:2048
	ds_read_b128 v[166:169], v150 offset:3072
	ds_read_b128 v[170:173], v151
	ds_read_b128 v[174:177], v151 offset:1024
	ds_read_b128 v[178:181], v151 offset:2048
	ds_read_b128 v[182:185], v151 offset:3072
	s_add_u32 s44, s42, 0xfff00080
	s_addc_u32 s45, s43, -1
	s_cmp_eq_u32 s68, 60
	s_cselect_b32 s47, s35, s45
	s_cselect_b32 s46, s64, s44
	s_cselect_b32 s45, s31, s67
	s_cselect_b32 s44, s65, s66
	s_add_i32 m0, s41, 0xc000
	ds_read_b128 v[186:189], v152
	ds_read_b128 v[190:193], v152 offset:1024
	ds_read_b128 v[198:201], v152 offset:2048
	ds_read_b128 v[202:205], v152 offset:3072
	ds_read_b128 v[206:209], v152 offset:4096
	ds_read_b128 v[210:213], v152 offset:5120
	ds_read_b128 v[214:217], v152 offset:6144
	ds_read_b128 v[218:221], v152 offset:7168
	global_load_lds_dwordx4 v138, s[42:43]
	s_add_i32 m0, s41, 0xe000
	s_nop 0
	global_load_lds_dwordx4 v140, s[42:43]
	s_waitcnt vmcnt(8)
	s_waitcnt lgkmcnt(0)
	s_barrier
	s_setprio 1
	s_waitcnt lgkmcnt(0)
	v_mfma_f32_16x16x32_bf16 v[126:129], v[154:157], v[186:189], v[126:129]
	v_mfma_f32_16x16x32_bf16 v[122:125], v[162:165], v[186:189], v[122:125]
	v_mfma_f32_16x16x32_bf16 v[110:113], v[154:157], v[198:201], v[110:113]
	v_mfma_f32_16x16x32_bf16 v[106:109], v[162:165], v[198:201], v[106:109]
	v_mfma_f32_16x16x32_bf16 v[94:97], v[154:157], v[206:209], v[94:97]
	v_mfma_f32_16x16x32_bf16 v[90:93], v[162:165], v[206:209], v[90:93]
	v_mfma_f32_16x16x32_bf16 v[78:81], v[154:157], v[214:217], v[78:81]
	v_mfma_f32_16x16x32_bf16 v[74:77], v[162:165], v[214:217], v[74:77]
	v_mfma_f32_16x16x32_bf16 v[126:129], v[158:161], v[190:193], v[126:129]
	v_mfma_f32_16x16x32_bf16 v[122:125], v[166:169], v[190:193], v[122:125]
	v_mfma_f32_16x16x32_bf16 v[110:113], v[158:161], v[202:205], v[110:113]
	v_mfma_f32_16x16x32_bf16 v[106:109], v[166:169], v[202:205], v[106:109]
	v_mfma_f32_16x16x32_bf16 v[94:97], v[158:161], v[210:213], v[94:97]
	v_mfma_f32_16x16x32_bf16 v[90:93], v[166:169], v[210:213], v[90:93]
	v_mfma_f32_16x16x32_bf16 v[78:81], v[158:161], v[218:221], v[78:81]
	v_mfma_f32_16x16x32_bf16 v[74:77], v[166:169], v[218:221], v[74:77]
	s_setprio 0
	s_setprio 1
	v_mfma_f32_16x16x32_bf16 v[118:121], v[170:173], v[186:189], v[118:121]
	v_mfma_f32_16x16x32_bf16 v[114:117], v[178:181], v[186:189], v[114:117]
	v_mfma_f32_16x16x32_bf16 v[102:105], v[170:173], v[198:201], v[102:105]
	v_mfma_f32_16x16x32_bf16 v[98:101], v[178:181], v[198:201], v[98:101]
	v_mfma_f32_16x16x32_bf16 v[86:89], v[170:173], v[206:209], v[86:89]
	v_mfma_f32_16x16x32_bf16 v[82:85], v[178:181], v[206:209], v[82:85]
	v_mfma_f32_16x16x32_bf16 v[70:73], v[170:173], v[214:217], v[70:73]
	v_mfma_f32_16x16x32_bf16 v[66:69], v[178:181], v[214:217], v[66:69]
	v_mfma_f32_16x16x32_bf16 v[118:121], v[174:177], v[190:193], v[118:121]
	v_mfma_f32_16x16x32_bf16 v[114:117], v[182:185], v[190:193], v[114:117]
	v_mfma_f32_16x16x32_bf16 v[102:105], v[174:177], v[202:205], v[102:105]
	v_mfma_f32_16x16x32_bf16 v[98:101], v[182:185], v[202:205], v[98:101]
	v_mfma_f32_16x16x32_bf16 v[86:89], v[174:177], v[210:213], v[86:89]
	v_mfma_f32_16x16x32_bf16 v[82:85], v[182:185], v[210:213], v[82:85]
	v_mfma_f32_16x16x32_bf16 v[70:73], v[174:177], v[218:221], v[70:73]
	v_mfma_f32_16x16x32_bf16 v[66:69], v[182:185], v[218:221], v[66:69]
	s_setprio 0
	s_barrier
	s_add_i32 s69, s57, s33
	s_mov_b32 m0, s69
	ds_read_b128 v[186:189], v152 offset:16384
	ds_read_b128 v[190:193], v152 offset:17408
	ds_read_b128 v[198:201], v152 offset:18432
	ds_read_b128 v[202:205], v152 offset:19456
	ds_read_b128 v[206:209], v152 offset:20480
	ds_read_b128 v[210:213], v152 offset:21504
	ds_read_b128 v[214:217], v152 offset:22528
	ds_read_b128 v[218:221], v152 offset:23552
	global_load_lds_dwordx4 v132, s[44:45]
	s_add_i32 m0, s69, 0x2000
	s_add_u32 s70, s44, 0x100000
	s_addc_u32 s71, s45, 0
	s_add_i32 s69, s58, s33
	global_load_lds_dwordx4 v136, s[44:45]
	s_mov_b32 m0, s69
	s_nop 0
	global_load_lds_dwordx4 v132, s[70:71]
	s_add_i32 m0, s69, 0x2000
	s_nop 0
	global_load_lds_dwordx4 v136, s[70:71]
	s_mov_b32 m0, s41
	s_nop 0
	global_load_lds_dwordx4 v130, s[46:47]
	s_mov_b32 m0, s50
	s_nop 0
	global_load_lds_dwordx4 v134, s[46:47]
	s_waitcnt vmcnt(8)
	s_waitcnt lgkmcnt(0)
	s_barrier
	s_setprio 1
	s_waitcnt lgkmcnt(0)
	v_mfma_f32_16x16x32_bf16 v[62:65], v[154:157], v[186:189], v[62:65]
	v_mfma_f32_16x16x32_bf16 v[58:61], v[162:165], v[186:189], v[58:61]
	v_mfma_f32_16x16x32_bf16 v[46:49], v[154:157], v[198:201], v[46:49]
	v_mfma_f32_16x16x32_bf16 v[42:45], v[162:165], v[198:201], v[42:45]
	v_mfma_f32_16x16x32_bf16 v[30:33], v[154:157], v[206:209], v[30:33]
	v_mfma_f32_16x16x32_bf16 v[26:29], v[162:165], v[206:209], v[26:29]
	v_mfma_f32_16x16x32_bf16 v[14:17], v[154:157], v[214:217], v[14:17]
	v_mfma_f32_16x16x32_bf16 v[10:13], v[162:165], v[214:217], v[10:13]
	v_mfma_f32_16x16x32_bf16 v[62:65], v[158:161], v[190:193], v[62:65]
	v_mfma_f32_16x16x32_bf16 v[58:61], v[166:169], v[190:193], v[58:61]
	v_mfma_f32_16x16x32_bf16 v[46:49], v[158:161], v[202:205], v[46:49]
	v_mfma_f32_16x16x32_bf16 v[42:45], v[166:169], v[202:205], v[42:45]
	v_mfma_f32_16x16x32_bf16 v[30:33], v[158:161], v[210:213], v[30:33]
	v_mfma_f32_16x16x32_bf16 v[26:29], v[166:169], v[210:213], v[26:29]
	v_mfma_f32_16x16x32_bf16 v[14:17], v[158:161], v[218:221], v[14:17]
	v_mfma_f32_16x16x32_bf16 v[10:13], v[166:169], v[218:221], v[10:13]
	s_setprio 0
	s_setprio 1
	v_mfma_f32_16x16x32_bf16 v[54:57], v[170:173], v[186:189], v[54:57]
	v_mfma_f32_16x16x32_bf16 v[50:53], v[178:181], v[186:189], v[50:53]
	v_mfma_f32_16x16x32_bf16 v[38:41], v[170:173], v[198:201], v[38:41]
	v_mfma_f32_16x16x32_bf16 v[34:37], v[178:181], v[198:201], v[34:37]
	v_mfma_f32_16x16x32_bf16 v[22:25], v[170:173], v[206:209], v[22:25]
	v_mfma_f32_16x16x32_bf16 v[18:21], v[178:181], v[206:209], v[18:21]
	v_mfma_f32_16x16x32_bf16 v[6:9], v[170:173], v[214:217], v[6:9]
	v_mfma_f32_16x16x32_bf16 v[2:5], v[178:181], v[214:217], v[2:5]
	v_mfma_f32_16x16x32_bf16 v[54:57], v[174:177], v[190:193], v[54:57]
	v_mfma_f32_16x16x32_bf16 v[50:53], v[182:185], v[190:193], v[50:53]
	v_mfma_f32_16x16x32_bf16 v[38:41], v[174:177], v[202:205], v[38:41]
	v_mfma_f32_16x16x32_bf16 v[34:37], v[182:185], v[202:205], v[34:37]
	v_mfma_f32_16x16x32_bf16 v[22:25], v[174:177], v[210:213], v[22:25]
	v_mfma_f32_16x16x32_bf16 v[18:21], v[182:185], v[210:213], v[18:21]
	v_mfma_f32_16x16x32_bf16 v[6:9], v[174:177], v[218:221], v[6:9]
	v_mfma_f32_16x16x32_bf16 v[2:5], v[182:185], v[218:221], v[2:5]
	s_setprio 0
	s_barrier
	s_add_i32 s69, 0, 0x18000
	s_add_i32 s70, 0, 0x1c000
	ds_read_b128 v[154:157], v150 offset:32768
	ds_read_b128 v[158:161], v150 offset:33792
	ds_read_b128 v[162:165], v150 offset:34816
	ds_read_b128 v[166:169], v150 offset:35840
	ds_read_b128 v[170:173], v150 offset:49152
	ds_read_b128 v[174:177], v150 offset:50176
	ds_read_b128 v[178:181], v150 offset:51200
	ds_read_b128 v[182:185], v150 offset:52224
	s_add_u32 s46, s46, 0x100000
	s_addc_u32 s47, s47, 0
	s_mov_b32 m0, s51
	ds_read_b128 v[186:189], v152 offset:32768
	ds_read_b128 v[190:193], v152 offset:33792
	ds_read_b128 v[198:201], v152 offset:34816
	ds_read_b128 v[202:205], v152 offset:35840
	ds_read_b128 v[206:209], v152 offset:36864
	ds_read_b128 v[210:213], v152 offset:37888
	ds_read_b128 v[214:217], v152 offset:38912
	ds_read_b128 v[218:221], v152 offset:39936
	global_load_lds_dwordx4 v130, s[46:47]
	s_mov_b32 m0, s52
	s_nop 0
	global_load_lds_dwordx4 v134, s[46:47]
	s_waitcnt vmcnt(8)
	s_waitcnt lgkmcnt(0)
	s_barrier
	s_setprio 1
	s_waitcnt lgkmcnt(0)
	v_mfma_f32_16x16x32_bf16 v[126:129], v[154:157], v[186:189], v[126:129]
	v_mfma_f32_16x16x32_bf16 v[122:125], v[162:165], v[186:189], v[122:125]
	v_mfma_f32_16x16x32_bf16 v[110:113], v[154:157], v[198:201], v[110:113]
	v_mfma_f32_16x16x32_bf16 v[106:109], v[162:165], v[198:201], v[106:109]
	v_mfma_f32_16x16x32_bf16 v[94:97], v[154:157], v[206:209], v[94:97]
	v_mfma_f32_16x16x32_bf16 v[90:93], v[162:165], v[206:209], v[90:93]
	v_mfma_f32_16x16x32_bf16 v[78:81], v[154:157], v[214:217], v[78:81]
	v_mfma_f32_16x16x32_bf16 v[74:77], v[162:165], v[214:217], v[74:77]
	v_mfma_f32_16x16x32_bf16 v[126:129], v[158:161], v[190:193], v[126:129]
	v_mfma_f32_16x16x32_bf16 v[122:125], v[166:169], v[190:193], v[122:125]
	v_mfma_f32_16x16x32_bf16 v[110:113], v[158:161], v[202:205], v[110:113]
	v_mfma_f32_16x16x32_bf16 v[106:109], v[166:169], v[202:205], v[106:109]
	v_mfma_f32_16x16x32_bf16 v[94:97], v[158:161], v[210:213], v[94:97]
	v_mfma_f32_16x16x32_bf16 v[90:93], v[166:169], v[210:213], v[90:93]
	v_mfma_f32_16x16x32_bf16 v[78:81], v[158:161], v[218:221], v[78:81]
	v_mfma_f32_16x16x32_bf16 v[74:77], v[166:169], v[218:221], v[74:77]
	s_setprio 0
	s_setprio 1
	v_mfma_f32_16x16x32_bf16 v[118:121], v[170:173], v[186:189], v[118:121]
	v_mfma_f32_16x16x32_bf16 v[114:117], v[178:181], v[186:189], v[114:117]
	v_mfma_f32_16x16x32_bf16 v[102:105], v[170:173], v[198:201], v[102:105]
	v_mfma_f32_16x16x32_bf16 v[98:101], v[178:181], v[198:201], v[98:101]
	v_mfma_f32_16x16x32_bf16 v[86:89], v[170:173], v[206:209], v[86:89]
	v_mfma_f32_16x16x32_bf16 v[82:85], v[178:181], v[206:209], v[82:85]
	v_mfma_f32_16x16x32_bf16 v[70:73], v[170:173], v[214:217], v[70:73]
	v_mfma_f32_16x16x32_bf16 v[66:69], v[178:181], v[214:217], v[66:69]
	v_mfma_f32_16x16x32_bf16 v[118:121], v[174:177], v[190:193], v[118:121]
	v_mfma_f32_16x16x32_bf16 v[114:117], v[182:185], v[190:193], v[114:117]
	v_mfma_f32_16x16x32_bf16 v[102:105], v[174:177], v[202:205], v[102:105]
	v_mfma_f32_16x16x32_bf16 v[98:101], v[182:185], v[202:205], v[98:101]
	v_mfma_f32_16x16x32_bf16 v[86:89], v[174:177], v[210:213], v[86:89]
	v_mfma_f32_16x16x32_bf16 v[82:85], v[182:185], v[210:213], v[82:85]
	v_mfma_f32_16x16x32_bf16 v[70:73], v[174:177], v[218:221], v[70:73]
	v_mfma_f32_16x16x32_bf16 v[66:69], v[182:185], v[218:221], v[66:69]
	s_setprio 0
	s_barrier
	s_add_i32 s71, s69, s33
	s_add_u32 s44, s44, 0x80
	s_addc_u32 s45, s45, 0
	s_mov_b32 m0, s71
	ds_read_b128 v[186:189], v152 offset:49152
	ds_read_b128 v[190:193], v152 offset:50176
	ds_read_b128 v[198:201], v152 offset:51200
	ds_read_b128 v[202:205], v152 offset:52224
	ds_read_b128 v[206:209], v152 offset:53248
	ds_read_b128 v[210:213], v152 offset:54272
	ds_read_b128 v[214:217], v152 offset:55296
	ds_read_b128 v[218:221], v152 offset:56320
	global_load_lds_dwordx4 v132, s[44:45]
	s_add_i32 m0, s71, 0x2000
	s_add_i32 s71, s70, s33
	s_add_u32 s46, s46, 0xfff00080
	global_load_lds_dwordx4 v136, s[44:45]
	s_addc_u32 s47, s47, -1
	s_add_u32 s44, s44, 0x100000
	s_addc_u32 s45, s45, 0
	s_mov_b32 m0, s71
	s_nop 0
	global_load_lds_dwordx4 v132, s[44:45]
	s_add_i32 m0, s71, 0x2000
	s_nop 0
	global_load_lds_dwordx4 v136, s[44:45]
	s_mov_b32 m0, s55
	s_nop 0
	global_load_lds_dwordx4 v130, s[46:47]
	s_mov_b32 m0, s56
	s_nop 0
	global_load_lds_dwordx4 v134, s[46:47]
	s_waitcnt vmcnt(8)
	s_waitcnt lgkmcnt(0)
	s_barrier
	s_setprio 1
	s_waitcnt lgkmcnt(0)
	v_mfma_f32_16x16x32_bf16 v[62:65], v[154:157], v[186:189], v[62:65]
	v_mfma_f32_16x16x32_bf16 v[58:61], v[162:165], v[186:189], v[58:61]
	v_mfma_f32_16x16x32_bf16 v[46:49], v[154:157], v[198:201], v[46:49]
	v_mfma_f32_16x16x32_bf16 v[42:45], v[162:165], v[198:201], v[42:45]
	v_mfma_f32_16x16x32_bf16 v[30:33], v[154:157], v[206:209], v[30:33]
	v_mfma_f32_16x16x32_bf16 v[26:29], v[162:165], v[206:209], v[26:29]
	v_mfma_f32_16x16x32_bf16 v[14:17], v[154:157], v[214:217], v[14:17]
	v_mfma_f32_16x16x32_bf16 v[10:13], v[162:165], v[214:217], v[10:13]
	v_mfma_f32_16x16x32_bf16 v[62:65], v[158:161], v[190:193], v[62:65]
	v_mfma_f32_16x16x32_bf16 v[58:61], v[166:169], v[190:193], v[58:61]
	v_mfma_f32_16x16x32_bf16 v[46:49], v[158:161], v[202:205], v[46:49]
	v_mfma_f32_16x16x32_bf16 v[42:45], v[166:169], v[202:205], v[42:45]
	v_mfma_f32_16x16x32_bf16 v[30:33], v[158:161], v[210:213], v[30:33]
	v_mfma_f32_16x16x32_bf16 v[26:29], v[166:169], v[210:213], v[26:29]
	v_mfma_f32_16x16x32_bf16 v[14:17], v[158:161], v[218:221], v[14:17]
	v_mfma_f32_16x16x32_bf16 v[10:13], v[166:169], v[218:221], v[10:13]
	s_setprio 0
	s_setprio 1
	v_mfma_f32_16x16x32_bf16 v[54:57], v[170:173], v[186:189], v[54:57]
	v_mfma_f32_16x16x32_bf16 v[50:53], v[178:181], v[186:189], v[50:53]
	v_mfma_f32_16x16x32_bf16 v[38:41], v[170:173], v[198:201], v[38:41]
	v_mfma_f32_16x16x32_bf16 v[34:37], v[178:181], v[198:201], v[34:37]
	v_mfma_f32_16x16x32_bf16 v[22:25], v[170:173], v[206:209], v[22:25]
	v_mfma_f32_16x16x32_bf16 v[18:21], v[178:181], v[206:209], v[18:21]
	v_mfma_f32_16x16x32_bf16 v[6:9], v[170:173], v[214:217], v[6:9]
	v_mfma_f32_16x16x32_bf16 v[2:5], v[178:181], v[214:217], v[2:5]
	v_mfma_f32_16x16x32_bf16 v[54:57], v[174:177], v[190:193], v[54:57]
	v_mfma_f32_16x16x32_bf16 v[50:53], v[182:185], v[190:193], v[50:53]
	v_mfma_f32_16x16x32_bf16 v[38:41], v[174:177], v[202:205], v[38:41]
	v_mfma_f32_16x16x32_bf16 v[34:37], v[182:185], v[202:205], v[34:37]
	v_mfma_f32_16x16x32_bf16 v[22:25], v[174:177], v[210:213], v[22:25]
	v_mfma_f32_16x16x32_bf16 v[18:21], v[182:185], v[210:213], v[18:21]
	v_mfma_f32_16x16x32_bf16 v[6:9], v[174:177], v[218:221], v[6:9]
	v_mfma_f32_16x16x32_bf16 v[2:5], v[182:185], v[218:221], v[2:5]
	s_setprio 0
	s_barrier
	s_add_i32 s68, s68, 2
	s_add_u32 s42, s42, 0x100
	s_addc_u32 s43, s43, 0
	s_add_u32 s66, s66, 0x100
	s_addc_u32 s67, s67, 0
	s_cmp_gt_u32 s68, 61
	s_cbranch_scc0 .LBB0_807
	s_and_b64 vcc, exec, s[14:15]
	s_cbranch_vccz .LBB0_810
	s_barrier
